# group-barrier census: 16 per-XCC counter loads issued together (one round trip) instead of one waited load each
# speedup vs baseline: 1.0024x; 1.0024x over previous
.LBB0_219:
	v_readlane_b32 s16, v252, 37
	v_readlane_b32 s17, v252, 38
	s_mov_b64 s[20:21], -1
	s_mov_b64 s[28:29], -1
	s_waitcnt lgkmcnt(0)
	s_nop 4
	global_load_dword v2, v27, s[16:17] sc1
	global_load_dword v3, v27, s[16:17] offset:256 sc1
	global_load_dword v4, v27, s[16:17] offset:512 sc1
	global_load_dword v5, v27, s[16:17] offset:768 sc1
	global_load_dword v6, v27, s[16:17] offset:1024 sc1
	global_load_dword v7, v27, s[16:17] offset:1280 sc1
	global_load_dword v8, v27, s[16:17] offset:1536 sc1
	global_load_dword v9, v27, s[16:17] offset:1792 sc1
	global_load_dword v10, v27, s[16:17] offset:2048 sc1
	global_load_dword v11, v27, s[16:17] offset:2304 sc1
	global_load_dword v12, v27, s[16:17] offset:2560 sc1
	global_load_dword v13, v27, s[16:17] offset:2816 sc1
	global_load_dword v14, v27, s[16:17] offset:3072 sc1
	global_load_dword v15, v27, s[16:17] offset:3328 sc1
	global_load_dword v16, v27, s[16:17] offset:3584 sc1
	global_load_dword v17, v27, s[16:17] offset:3840 sc1
	s_waitcnt vmcnt(0)
	v_add_u32_e32 v18, v3, v2
	v_add_u32_e32 v18, v18, v4
	v_add_u32_e32 v18, v18, v5
	v_add_u32_e32 v18, v18, v6
	v_add_u32_e32 v18, v18, v7
	v_add_u32_e32 v18, v18, v8
	v_add_u32_e32 v18, v18, v9
	v_add_u32_e32 v18, v18, v10
	v_add_u32_e32 v18, v18, v11
	v_add_u32_e32 v18, v18, v12
	v_add_u32_e32 v18, v18, v13
	v_add_u32_e32 v18, v18, v14
	v_add_u32_e32 v18, v18, v15
	v_add_u32_e32 v18, v18, v16
	v_add_u32_e32 v18, v18, v17
	v_cmp_eq_u32_e32 vcc, s4, v18
	s_cbranch_vccnz .LBB0_218
	s_and_b32 s12, s11, 0xff
	s_cmp_eq_u32 s12, 0
	s_mov_b64 s[30:31], -1
	s_sleep 1
	s_cbranch_scc0 .LBB0_223
	v_readlane_b32 s16, v252, 35
	v_readlane_b32 s17, v252, 36
	s_nop 4
	global_load_dword v18, v27, s[16:17] sc1
	s_waitcnt vmcnt(0)
	v_cmp_eq_u32_e32 vcc, 0, v18
	s_cbranch_vccnz .LBB0_225
	s_mov_b64 s[30:31], 0

.LBB0_479:
	v_add_co_u32_e32 v20, vcc, 0x1000, v18
	s_mov_b32 s0, 0x12000
	s_nop 0
	v_addc_co_u32_e32 v21, vcc, 0, v19, vcc
	v_add_co_u32_e32 v22, vcc, 0x4000, v18
	s_waitcnt vmcnt(0)
	v_lshlrev_b32_e32 v152, 16, v112
	v_addc_co_u32_e32 v23, vcc, 0, v19, vcc
	v_add_co_u32_e32 v24, vcc, 0x6000, v18
	v_and_b32_e32 v153, 0xffff0000, v112
	s_nop 0
	v_addc_co_u32_e32 v25, vcc, 0, v19, vcc
	v_add_co_u32_e32 v28, vcc, 0x7000, v18
	v_lshlrev_b32_e32 v112, 16, v113
	s_nop 0
	v_addc_co_u32_e32 v29, vcc, 0, v19, vcc
	v_add_co_u32_e32 v30, vcc, 0x9000, v18
	global_load_dwordx2 v[138:139], v[20:21], off offset:1024
	global_load_dwordx2 v[140:141], v[20:21], off offset:3072
	global_load_dwordx2 v[142:143], v[22:23], off
	global_load_dwordx2 v[144:145], v[20:21], off offset:2048
	global_load_dwordx2 v[146:147], v[18:19], off offset:1024
	global_load_dwordx2 v[148:149], v[22:23], off offset:2048
	global_load_dwordx2 v[96:97], v[24:25], off offset:3072
	global_load_dwordx2 v[94:95], v[28:29], off
	global_load_dwordx2 v[108:109], v[22:23], off offset:1024
	v_addc_co_u32_e32 v31, vcc, 0, v19, vcc
	v_add_co_u32_e32 v32, vcc, 0xa000, v18
	v_and_b32_e32 v113, 0xffff0000, v113
	s_nop 0
	v_addc_co_u32_e32 v33, vcc, 0, v19, vcc
	v_add_co_u32_e32 v34, vcc, 0xc000, v18
	global_load_dwordx2 v[100:101], v[28:29], off offset:1024
	global_load_dwordx2 v[90:91], v[30:31], off offset:2048
	global_load_dwordx2 v[66:67], v[32:33], off
	global_load_dwordx2 v[64:65], v[30:31], off offset:3072
	v_addc_co_u32_e32 v35, vcc, 0, v19, vcc
	v_add_co_u32_e32 v38, vcc, 0xf000, v18
	s_nop 1
	v_addc_co_u32_e32 v39, vcc, 0, v19, vcc
	v_add_co_u32_e32 v36, vcc, 0x11000, v18
	global_load_dwordx2 v[60:61], v[34:35], off offset:1024
	global_load_dwordx2 v[58:59], v[34:35], off offset:3072
	global_load_dwordx2 v[46:47], v[38:39], off
	global_load_dwordx2 v[54:55], v[34:35], off offset:2048
	v_addc_co_u32_e32 v37, vcc, 0, v19, vcc
	v_add_co_u32_e32 v40, vcc, s0, v18
	s_mov_b32 s0, 0x14000
	s_nop 0
	v_addc_co_u32_e32 v41, vcc, 0, v19, vcc
	v_add_co_u32_e32 v52, vcc, s0, v18
	s_movk_i32 s0, 0x5000
	s_nop 0
	v_addc_co_u32_e32 v53, vcc, 0, v19, vcc
	v_add_co_u32_e32 v136, vcc, 0x15000, v18
	s_nop 1
	v_addc_co_u32_e32 v137, vcc, 0, v19, vcc
	v_add_co_u32_e32 v102, vcc, 0x3000, v18
	s_nop 1
	v_addc_co_u32_e32 v103, vcc, 0, v19, vcc
	v_add_co_u32_e32 v92, vcc, s0, v18
	s_mov_b32 s0, 0x8000
	s_nop 0
	v_addc_co_u32_e32 v93, vcc, 0, v19, vcc
	v_add_co_u32_e32 v62, vcc, s0, v18
	s_mov_b32 s0, 0xb000
	s_nop 0
	v_addc_co_u32_e32 v63, vcc, 0, v19, vcc
	v_add_co_u32_e32 v50, vcc, s0, v18
	s_mov_b32 s0, 0xe000
	s_nop 0
	v_addc_co_u32_e32 v51, vcc, 0, v19, vcc
	global_load_dwordx2 v[150:151], v[102:103], off
	global_load_dwordx2 v[104:105], v[92:93], off offset:3072
	global_load_dwordx2 v[88:89], v[62:63], off offset:2048
	global_load_dwordx2 v[56:57], v[50:51], off offset:1024
	global_load_dwordx2 v[48:49], v[38:39], off offset:2048
	s_nop 0
	global_load_dwordx2 v[36:37], v[36:37], off offset:3072
	s_nop 0
	global_load_dwordx2 v[34:35], v[40:41], off
	global_load_dwordx2 v[44:45], v[38:39], off offset:1024
	v_add_co_u32_e32 v42, vcc, s0, v18
	s_mov_b32 s0, 0x10000
	s_nop 0
	v_addc_co_u32_e32 v43, vcc, 0, v19, vcc
	v_add_co_u32_e32 v32, vcc, s0, v18
	s_mov_b32 s0, 0x13000
	s_nop 0
	v_addc_co_u32_e32 v33, vcc, 0, v19, vcc
	v_add_co_u32_e32 v20, vcc, s0, v18
	global_load_dwordx2 v[40:41], v[40:41], off offset:1024
	s_nop 0
	global_load_dwordx2 v[30:31], v[52:53], off offset:2048
	global_load_dwordx2 v[28:29], v[136:137], off
	global_load_dwordx2 v[22:23], v[52:53], off offset:3072
	v_addc_co_u32_e32 v21, vcc, 0, v19, vcc
	global_load_dwordx2 v[52:53], v[42:43], off
	global_load_dwordx2 v[38:39], v[32:33], off offset:3072
	global_load_dwordx2 v[24:25], v[20:21], off offset:2048
	v_lshlrev_b32_e32 v136, 16, v110
	v_and_b32_e32 v137, 0xffff0000, v110
	v_lshlrev_b32_e32 v110, 16, v111
	v_and_b32_e32 v111, 0xffff0000, v111
	v_pk_mul_f32 v[136:137], v[136:137], v[152:153]
	v_pk_mul_f32 v[110:111], v[110:111], v[112:113]
	v_lshlrev_b32_e32 v112, 16, v98
	v_and_b32_e32 v113, 0xffff0000, v98
	v_lshlrev_b32_e32 v152, 16, v106
	v_and_b32_e32 v153, 0xffff0000, v106
	v_lshlrev_b32_e32 v98, 16, v99
	v_and_b32_e32 v99, 0xffff0000, v99
	v_lshlrev_b32_e32 v106, 16, v107
	v_and_b32_e32 v107, 0xffff0000, v107
	v_pk_mul_f32 v[112:113], v[112:113], v[152:153]
	v_pk_mul_f32 v[98:99], v[98:99], v[106:107]
	s_waitcnt vmcnt(31)
	v_lshlrev_b32_e32 v106, 16, v138
	v_and_b32_e32 v107, 0xffff0000, v138
	s_waitcnt vmcnt(30)
	v_lshlrev_b32_e32 v152, 16, v140
	v_and_b32_e32 v153, 0xffff0000, v140
	v_pk_mul_f32 v[106:107], v[106:107], v[152:153]
	s_waitcnt vmcnt(27)
	v_lshlrev_b32_e32 v152, 16, v146
	v_and_b32_e32 v153, 0xffff0000, v146
	v_pk_mul_f32 v[154:155], v[152:153], s[24:25] op_sel_hi:[1,0]
	v_lshlrev_b32_e32 v146, 16, v147
	v_and_b32_e32 v147, 0xffff0000, v147
	v_exp_f32_e32 v154, v154
	v_exp_f32_e32 v155, v155
	v_pk_mul_f32 v[156:157], v[146:147], s[24:25] op_sel_hi:[1,0]
	v_pk_fma_f32 v[112:113], v[10:11], v[112:113], v[14:15]
	v_exp_f32_e32 v156, v156
	v_exp_f32_e32 v157, v157
	v_pk_add_f32 v[154:155], v[154:155], 1.0 op_sel_hi:[1,0]
	v_lshlrev_b32_e32 v138, 16, v139
	v_rcp_f32_e32 v154, v154
	v_rcp_f32_e32 v155, v155
	v_pk_add_f32 v[156:157], v[156:157], 1.0 op_sel_hi:[1,0]
	v_and_b32_e32 v139, 0xffff0000, v139
	v_rcp_f32_e32 v156, v156
	v_rcp_f32_e32 v157, v157
	v_lshlrev_b32_e32 v140, 16, v141
	v_and_b32_e32 v141, 0xffff0000, v141
	v_pk_fma_f32 v[98:99], v[12:13], v[98:99], v[16:17]
	v_pk_fma_f32 v[112:113], v[2:3], v[136:137], v[112:113]
	v_pk_mul_f32 v[138:139], v[138:139], v[140:141]
	v_pk_fma_f32 v[98:99], v[4:5], v[110:111], v[98:99]
	v_pk_fma_f32 v[112:113], v[6:7], v[106:107], v[112:113]
	v_lshlrev_b32_e32 v140, 16, v144
	v_and_b32_e32 v141, 0xffff0000, v144
	v_pk_fma_f32 v[98:99], v[8:9], v[138:139], v[98:99]
	v_lshlrev_b32_e32 v144, 16, v145
	v_and_b32_e32 v145, 0xffff0000, v145
	v_pk_mul_f32 v[152:153], v[154:155], v[152:153]
	v_pk_mul_f32 v[112:113], v[112:113], v[140:141]
	v_pk_mul_f32 v[146:147], v[156:157], v[146:147]
	v_pk_mul_f32 v[98:99], v[98:99], v[144:145]
	v_pk_mul_f32 v[112:113], v[112:113], v[152:153]
	v_pk_mul_f32 v[98:99], v[98:99], v[146:147]
	v_cvt_pk_bf16_f32 v112, v112, v113
	s_waitcnt vmcnt(14)
	v_lshlrev_b32_e32 v146, 16, v151
	v_cvt_pk_bf16_f32 v113, v98, v99
	global_store_dwordx2 v[18:19], v[112:113], off offset:1024
	v_lshlrev_b32_e32 v98, 16, v142
	v_and_b32_e32 v99, 0xffff0000, v142
	v_lshlrev_b32_e32 v112, 16, v148
	v_and_b32_e32 v113, 0xffff0000, v148
	v_pk_mul_f32 v[98:99], v[98:99], v[112:113]
	v_lshlrev_b32_e32 v112, 16, v143
	v_and_b32_e32 v113, 0xffff0000, v143
	v_lshlrev_b32_e32 v142, 16, v150
	v_and_b32_e32 v143, 0xffff0000, v150
	v_pk_mul_f32 v[144:145], v[142:143], s[24:25] op_sel_hi:[1,0]
	v_and_b32_e32 v147, 0xffff0000, v151
	v_lshlrev_b32_e32 v140, 16, v149
	v_and_b32_e32 v141, 0xffff0000, v149
	v_exp_f32_e32 v144, v144
	v_exp_f32_e32 v145, v145
	v_pk_mul_f32 v[148:149], v[146:147], s[24:25] op_sel_hi:[1,0]
	v_pk_fma_f32 v[136:137], v[10:11], v[136:137], v[14:15]
	v_exp_f32_e32 v148, v148
	v_exp_f32_e32 v149, v149
	v_pk_add_f32 v[144:145], v[144:145], 1.0 op_sel_hi:[1,0]
	v_pk_fma_f32 v[110:111], v[12:13], v[110:111], v[16:17]
	v_rcp_f32_e32 v144, v144
	v_rcp_f32_e32 v145, v145
	v_pk_add_f32 v[148:149], v[148:149], 1.0 op_sel_hi:[1,0]
	v_pk_fma_f32 v[136:137], v[2:3], v[106:107], v[136:137]
	v_rcp_f32_e32 v148, v148
	v_rcp_f32_e32 v149, v149
	v_pk_mul_f32 v[112:113], v[112:113], v[140:141]
	v_pk_fma_f32 v[110:111], v[4:5], v[138:139], v[110:111]
	v_pk_fma_f32 v[136:137], v[6:7], v[98:99], v[136:137]
	v_lshlrev_b32_e32 v140, 16, v108
	v_and_b32_e32 v141, 0xffff0000, v108
	v_pk_fma_f32 v[110:111], v[8:9], v[112:113], v[110:111]
	v_lshlrev_b32_e32 v108, 16, v109
	v_and_b32_e32 v109, 0xffff0000, v109
	v_pk_mul_f32 v[142:143], v[144:145], v[142:143]
	v_pk_mul_f32 v[136:137], v[136:137], v[140:141]
	v_pk_mul_f32 v[144:145], v[148:149], v[146:147]
	v_pk_mul_f32 v[108:109], v[110:111], v[108:109]
	v_pk_mul_f32 v[110:111], v[136:137], v[142:143]
	v_pk_mul_f32 v[108:109], v[108:109], v[144:145]
	v_cvt_pk_bf16_f32 v110, v110, v111
	v_pk_fma_f32 v[106:107], v[10:11], v[106:107], v[14:15]
	v_cvt_pk_bf16_f32 v111, v108, v109
	global_store_dwordx2 v[102:103], v[110:111], off
	s_waitcnt vmcnt(15)
	v_lshlrev_b32_e32 v110, 16, v104
	v_and_b32_e32 v111, 0xffff0000, v104
	v_lshlrev_b32_e32 v102, 16, v96
	v_and_b32_e32 v103, 0xffff0000, v96
	v_lshlrev_b32_e32 v108, 16, v100
	v_and_b32_e32 v109, 0xffff0000, v100
	v_lshlrev_b32_e32 v96, 16, v97
	v_and_b32_e32 v97, 0xffff0000, v97
	v_lshlrev_b32_e32 v100, 16, v101
	v_and_b32_e32 v101, 0xffff0000, v101
	v_pk_mul_f32 v[136:137], v[110:111], s[24:25] op_sel_hi:[1,0]
	v_lshlrev_b32_e32 v104, 16, v105
	v_and_b32_e32 v105, 0xffff0000, v105
	v_pk_mul_f32 v[96:97], v[96:97], v[100:101]
	v_pk_fma_f32 v[100:101], v[12:13], v[138:139], v[16:17]
	v_exp_f32_e32 v136, v136
	v_exp_f32_e32 v137, v137
	v_pk_mul_f32 v[138:139], v[104:105], s[24:25] op_sel_hi:[1,0]
	v_pk_mul_f32 v[102:103], v[102:103], v[108:109]
	v_exp_f32_e32 v138, v138
	v_exp_f32_e32 v139, v139
	v_pk_add_f32 v[136:137], v[136:137], 1.0 op_sel_hi:[1,0]
	v_pk_fma_f32 v[106:107], v[2:3], v[98:99], v[106:107]
	v_rcp_f32_e32 v136, v136
	v_rcp_f32_e32 v137, v137
	v_pk_add_f32 v[138:139], v[138:139], 1.0 op_sel_hi:[1,0]
	v_pk_fma_f32 v[100:101], v[4:5], v[112:113], v[100:101]
	v_rcp_f32_e32 v138, v138
	v_rcp_f32_e32 v139, v139
	v_pk_fma_f32 v[106:107], v[6:7], v[102:103], v[106:107]
	v_lshlrev_b32_e32 v108, 16, v94
	v_and_b32_e32 v109, 0xffff0000, v94
	v_pk_fma_f32 v[100:101], v[8:9], v[96:97], v[100:101]
	v_lshlrev_b32_e32 v94, 16, v95
	v_and_b32_e32 v95, 0xffff0000, v95
	v_pk_mul_f32 v[110:111], v[136:137], v[110:111]
	v_pk_mul_f32 v[106:107], v[106:107], v[108:109]
	v_pk_mul_f32 v[104:105], v[138:139], v[104:105]
	v_pk_mul_f32 v[94:95], v[100:101], v[94:95]
	v_pk_mul_f32 v[100:101], v[106:107], v[110:111]
	v_pk_mul_f32 v[94:95], v[94:95], v[104:105]
	v_cvt_pk_bf16_f32 v100, v100, v101
	s_mov_b32 s0, 0x17000
	v_cvt_pk_bf16_f32 v101, v94, v95
	global_store_dwordx2 v[92:93], v[100:101], off offset:3072
	s_waitcnt vmcnt(15)
	v_lshlrev_b32_e32 v100, 16, v88
	v_and_b32_e32 v101, 0xffff0000, v88
	v_lshlrev_b32_e32 v88, 16, v89
	v_and_b32_e32 v89, 0xffff0000, v89
	v_pk_mul_f32 v[104:105], v[100:101], s[24:25] op_sel_hi:[1,0]
	v_pk_mul_f32 v[106:107], v[88:89], s[24:25] op_sel_hi:[1,0]
	v_exp_f32_e32 v104, v104
	v_exp_f32_e32 v105, v105
	v_exp_f32_e32 v106, v106
	v_exp_f32_e32 v107, v107
	v_lshlrev_b32_e32 v92, 16, v90
	v_pk_add_f32 v[104:105], v[104:105], 1.0 op_sel_hi:[1,0]
	v_and_b32_e32 v93, 0xffff0000, v90
	v_pk_add_f32 v[106:107], v[106:107], 1.0 op_sel_hi:[1,0]
	v_lshlrev_b32_e32 v94, 16, v66
	v_and_b32_e32 v95, 0xffff0000, v66
	v_lshlrev_b32_e32 v90, 16, v91
	v_and_b32_e32 v91, 0xffff0000, v91
	v_lshlrev_b32_e32 v66, 16, v67
	v_and_b32_e32 v67, 0xffff0000, v67
	v_rcp_f32_e32 v104, v104
	v_rcp_f32_e32 v105, v105
	v_rcp_f32_e32 v106, v106
	v_rcp_f32_e32 v107, v107
	v_pk_mul_f32 v[92:93], v[92:93], v[94:95]
	v_pk_mul_f32 v[66:67], v[90:91], v[66:67]
	v_pk_fma_f32 v[90:91], v[12:13], v[112:113], v[16:17]
	v_pk_fma_f32 v[94:95], v[10:11], v[98:99], v[14:15]
	v_pk_fma_f32 v[90:91], v[4:5], v[96:97], v[90:91]
	v_pk_fma_f32 v[94:95], v[2:3], v[102:103], v[94:95]
	v_pk_fma_f32 v[90:91], v[8:9], v[66:67], v[90:91]
	v_pk_fma_f32 v[94:95], v[6:7], v[92:93], v[94:95]
	v_lshlrev_b32_e32 v98, 16, v64
	v_and_b32_e32 v99, 0xffff0000, v64
	v_lshlrev_b32_e32 v64, 16, v65
	v_and_b32_e32 v65, 0xffff0000, v65
	v_pk_mul_f32 v[100:101], v[104:105], v[100:101]
	v_pk_mul_f32 v[88:89], v[106:107], v[88:89]
	v_pk_mul_f32 v[94:95], v[94:95], v[98:99]
	v_pk_mul_f32 v[64:65], v[90:91], v[64:65]
	s_waitcnt vmcnt(14)
	v_lshlrev_b32_e32 v90, 16, v56
	v_pk_mul_f32 v[64:65], v[64:65], v[88:89]
	v_pk_mul_f32 v[88:89], v[94:95], v[100:101]
	v_and_b32_e32 v91, 0xffff0000, v56
	v_cvt_pk_bf16_f32 v88, v88, v89
	v_cvt_pk_bf16_f32 v89, v64, v65
	global_store_dwordx2 v[62:63], v[88:89], off offset:2048
	v_lshlrev_b32_e32 v62, 16, v60
	v_and_b32_e32 v63, 0xffff0000, v60
	v_lshlrev_b32_e32 v64, 16, v58
	v_and_b32_e32 v65, 0xffff0000, v58
	v_lshlrev_b32_e32 v60, 16, v61
	v_and_b32_e32 v61, 0xffff0000, v61
	v_lshlrev_b32_e32 v58, 16, v59
	v_and_b32_e32 v59, 0xffff0000, v59
	v_lshlrev_b32_e32 v56, 16, v57
	v_and_b32_e32 v57, 0xffff0000, v57
	v_pk_mul_f32 v[60:61], v[60:61], v[58:59]
	v_pk_fma_f32 v[58:59], v[12:13], v[96:97], v[16:17]
	v_pk_mul_f32 v[94:95], v[90:91], s[24:25] op_sel_hi:[1,0]
	v_pk_mul_f32 v[96:97], v[56:57], s[24:25] op_sel_hi:[1,0]
	v_exp_f32_e32 v94, v94
	v_exp_f32_e32 v95, v95
	v_exp_f32_e32 v96, v96
	v_exp_f32_e32 v97, v97
	v_pk_mul_f32 v[62:63], v[62:63], v[64:65]
	v_pk_add_f32 v[94:95], v[94:95], 1.0 op_sel_hi:[1,0]
	v_pk_fma_f32 v[64:65], v[10:11], v[102:103], v[14:15]
	v_pk_add_f32 v[96:97], v[96:97], 1.0 op_sel_hi:[1,0]
	v_rcp_f32_e32 v94, v94
	v_rcp_f32_e32 v95, v95
	v_rcp_f32_e32 v96, v96
	v_rcp_f32_e32 v97, v97
	v_pk_fma_f32 v[64:65], v[2:3], v[92:93], v[64:65]
	v_pk_fma_f32 v[58:59], v[4:5], v[66:67], v[58:59]
	v_pk_fma_f32 v[64:65], v[6:7], v[62:63], v[64:65]
	v_pk_fma_f32 v[58:59], v[8:9], v[60:61], v[58:59]
	v_lshlrev_b32_e32 v88, 16, v54
	v_and_b32_e32 v89, 0xffff0000, v54
	v_lshlrev_b32_e32 v54, 16, v55
	v_and_b32_e32 v55, 0xffff0000, v55
	v_pk_mul_f32 v[90:91], v[94:95], v[90:91]
	v_pk_mul_f32 v[56:57], v[96:97], v[56:57]
	v_pk_mul_f32 v[64:65], v[64:65], v[88:89]
	v_pk_mul_f32 v[54:55], v[58:59], v[54:55]
	s_waitcnt vmcnt(6)
	v_lshlrev_b32_e32 v58, 16, v52
	v_pk_mul_f32 v[54:55], v[54:55], v[56:57]
	v_pk_mul_f32 v[56:57], v[64:65], v[90:91]
	v_and_b32_e32 v59, 0xffff0000, v52
	v_cvt_pk_bf16_f32 v56, v56, v57
	v_cvt_pk_bf16_f32 v57, v54, v55
	global_store_dwordx2 v[50:51], v[56:57], off offset:1024
	v_lshlrev_b32_e32 v50, 16, v46
	v_and_b32_e32 v51, 0xffff0000, v46
	v_lshlrev_b32_e32 v54, 16, v48
	v_and_b32_e32 v55, 0xffff0000, v48
	v_lshlrev_b32_e32 v46, 16, v47
	v_and_b32_e32 v47, 0xffff0000, v47
	v_lshlrev_b32_e32 v48, 16, v49
	v_and_b32_e32 v49, 0xffff0000, v49
	v_lshlrev_b32_e32 v52, 16, v53
	v_and_b32_e32 v53, 0xffff0000, v53
	v_pk_mul_f32 v[46:47], v[46:47], v[48:49]
	v_pk_fma_f32 v[48:49], v[12:13], v[66:67], v[16:17]
	v_pk_mul_f32 v[64:65], v[58:59], s[24:25] op_sel_hi:[1,0]
	v_pk_mul_f32 v[66:67], v[52:53], s[24:25] op_sel_hi:[1,0]
	v_exp_f32_e32 v64, v64
	v_exp_f32_e32 v65, v65
	v_exp_f32_e32 v66, v66
	v_exp_f32_e32 v67, v67
	v_pk_mul_f32 v[50:51], v[50:51], v[54:55]
	v_pk_add_f32 v[64:65], v[64:65], 1.0 op_sel_hi:[1,0]
	v_pk_fma_f32 v[54:55], v[10:11], v[92:93], v[14:15]
	v_pk_add_f32 v[66:67], v[66:67], 1.0 op_sel_hi:[1,0]
	v_rcp_f32_e32 v64, v64
	v_rcp_f32_e32 v65, v65
	v_rcp_f32_e32 v66, v66
	v_rcp_f32_e32 v67, v67
	v_pk_fma_f32 v[54:55], v[2:3], v[62:63], v[54:55]
	v_pk_fma_f32 v[48:49], v[4:5], v[60:61], v[48:49]
	v_pk_fma_f32 v[54:55], v[6:7], v[50:51], v[54:55]
	v_pk_fma_f32 v[48:49], v[8:9], v[46:47], v[48:49]
	v_lshlrev_b32_e32 v56, 16, v44
	v_and_b32_e32 v57, 0xffff0000, v44
	v_lshlrev_b32_e32 v44, 16, v45
	v_and_b32_e32 v45, 0xffff0000, v45
	v_pk_mul_f32 v[58:59], v[64:65], v[58:59]
	v_pk_mul_f32 v[52:53], v[66:67], v[52:53]
	v_pk_mul_f32 v[54:55], v[54:55], v[56:57]
	v_pk_mul_f32 v[44:45], v[48:49], v[44:45]
	v_pk_mul_f32 v[48:49], v[54:55], v[58:59]
	v_pk_mul_f32 v[44:45], v[44:45], v[52:53]
	v_cvt_pk_bf16_f32 v48, v48, v49
	s_nop 0
	v_cvt_pk_bf16_f32 v49, v44, v45
	global_store_dwordx2 v[42:43], v[48:49], off
	v_lshlrev_b32_e32 v42, 16, v36
	v_and_b32_e32 v43, 0xffff0000, v36
	v_lshlrev_b32_e32 v44, 16, v40
	v_and_b32_e32 v45, 0xffff0000, v40
	v_pk_mul_f32 v[58:59], v[42:43], v[44:45]
	s_waitcnt vmcnt(7)
	v_lshlrev_b32_e32 v44, 16, v38
	v_and_b32_e32 v45, 0xffff0000, v38
	v_lshlrev_b32_e32 v38, 16, v39
	v_and_b32_e32 v39, 0xffff0000, v39
	v_pk_mul_f32 v[48:49], v[44:45], s[24:25] op_sel_hi:[1,0]
	v_pk_mul_f32 v[52:53], v[38:39], s[24:25] op_sel_hi:[1,0]
	v_exp_f32_e32 v48, v48
	v_exp_f32_e32 v49, v49
	v_exp_f32_e32 v52, v52
	v_exp_f32_e32 v53, v53
	v_lshlrev_b32_e32 v36, 16, v37
	v_pk_add_f32 v[48:49], v[48:49], 1.0 op_sel_hi:[1,0]
	v_and_b32_e32 v37, 0xffff0000, v37
	v_pk_add_f32 v[52:53], v[52:53], 1.0 op_sel_hi:[1,0]
	v_lshlrev_b32_e32 v40, 16, v41
	v_and_b32_e32 v41, 0xffff0000, v41
	v_rcp_f32_e32 v48, v48
	v_rcp_f32_e32 v49, v49
	v_rcp_f32_e32 v52, v52
	v_rcp_f32_e32 v53, v53
	v_pk_mul_f32 v[66:67], v[36:37], v[40:41]
	v_pk_fma_f32 v[36:37], v[12:13], v[60:61], v[16:17]
	v_pk_fma_f32 v[40:41], v[10:11], v[62:63], v[14:15]
	v_pk_fma_f32 v[36:37], v[4:5], v[46:47], v[36:37]
	v_pk_fma_f32 v[40:41], v[2:3], v[50:51], v[40:41]
	v_pk_fma_f32 v[36:37], v[8:9], v[66:67], v[36:37]
	v_pk_fma_f32 v[40:41], v[6:7], v[58:59], v[40:41]
	v_lshlrev_b32_e32 v42, 16, v34
	v_and_b32_e32 v43, 0xffff0000, v34
	v_lshlrev_b32_e32 v34, 16, v35
	v_and_b32_e32 v35, 0xffff0000, v35
	v_pk_mul_f32 v[44:45], v[48:49], v[44:45]
	v_pk_mul_f32 v[38:39], v[52:53], v[38:39]
	v_pk_mul_f32 v[40:41], v[40:41], v[42:43]
	v_pk_mul_f32 v[34:35], v[36:37], v[34:35]
	v_pk_mul_f32 v[36:37], v[40:41], v[44:45]
	v_pk_mul_f32 v[34:35], v[34:35], v[38:39]
	v_cvt_pk_bf16_f32 v36, v36, v37
	s_nop 0
	v_cvt_pk_bf16_f32 v37, v34, v35
	global_store_dwordx2 v[32:33], v[36:37], off offset:3072
	v_lshlrev_b32_e32 v32, 16, v30
	v_and_b32_e32 v33, 0xffff0000, v30
	v_lshlrev_b32_e32 v34, 16, v28
	v_and_b32_e32 v35, 0xffff0000, v28
	v_pk_mul_f32 v[60:61], v[32:33], v[34:35]
	s_waitcnt vmcnt(7)
	v_lshlrev_b32_e32 v34, 16, v24
	v_and_b32_e32 v35, 0xffff0000, v24
	v_lshlrev_b32_e32 v24, 16, v25
	v_and_b32_e32 v25, 0xffff0000, v25
	v_pk_mul_f32 v[36:37], v[34:35], s[24:25] op_sel_hi:[1,0]
	v_pk_mul_f32 v[38:39], v[24:25], s[24:25] op_sel_hi:[1,0]
	v_exp_f32_e32 v36, v36
	v_exp_f32_e32 v37, v37
	v_exp_f32_e32 v38, v38
	v_exp_f32_e32 v39, v39
	v_lshlrev_b32_e32 v30, 16, v31
	v_pk_add_f32 v[36:37], v[36:37], 1.0 op_sel_hi:[1,0]
	v_and_b32_e32 v31, 0xffff0000, v31
	v_pk_add_f32 v[38:39], v[38:39], 1.0 op_sel_hi:[1,0]
	v_lshlrev_b32_e32 v28, 16, v29
	v_and_b32_e32 v29, 0xffff0000, v29
	v_rcp_f32_e32 v36, v36
	v_rcp_f32_e32 v37, v37
	v_rcp_f32_e32 v38, v38
	v_rcp_f32_e32 v39, v39
	v_pk_mul_f32 v[88:89], v[30:31], v[28:29]
	v_pk_fma_f32 v[28:29], v[12:13], v[46:47], v[16:17]
	v_pk_fma_f32 v[30:31], v[10:11], v[50:51], v[14:15]
	v_pk_fma_f32 v[28:29], v[4:5], v[66:67], v[28:29]
	v_pk_fma_f32 v[30:31], v[2:3], v[58:59], v[30:31]
	v_pk_fma_f32 v[28:29], v[8:9], v[88:89], v[28:29]
	v_pk_fma_f32 v[30:31], v[6:7], v[60:61], v[30:31]
	v_lshlrev_b32_e32 v32, 16, v22
	v_and_b32_e32 v33, 0xffff0000, v22
	v_lshlrev_b32_e32 v22, 16, v23
	v_and_b32_e32 v23, 0xffff0000, v23
	v_pk_mul_f32 v[34:35], v[36:37], v[34:35]
	v_pk_mul_f32 v[24:25], v[38:39], v[24:25]
	v_pk_mul_f32 v[30:31], v[30:31], v[32:33]
	v_pk_mul_f32 v[22:23], v[28:29], v[22:23]
	v_pk_fma_f32 v[58:59], v[10:11], v[58:59], v[14:15]
	v_pk_mul_f32 v[22:23], v[22:23], v[24:25]
	v_pk_mul_f32 v[24:25], v[30:31], v[34:35]
	v_pk_fma_f32 v[66:67], v[12:13], v[66:67], v[16:17]
	v_cvt_pk_bf16_f32 v24, v24, v25
	v_cvt_pk_bf16_f32 v25, v22, v23
	global_store_dwordx2 v[20:21], v[24:25], off offset:2048
	v_add_co_u32_e32 v20, vcc, s0, v18
	s_mov_b32 s0, 0x1a000
	s_nop 0
	v_addc_co_u32_e32 v21, vcc, 0, v19, vcc
	v_add_co_u32_e32 v32, vcc, s0, v18
	s_mov_b32 s0, 0x1c000
	s_nop 0
	v_addc_co_u32_e32 v33, vcc, 0, v19, vcc
	v_add_co_u32_e32 v34, vcc, s0, v18
	s_mov_b32 s0, 0x1d000
	s_nop 0
	v_addc_co_u32_e32 v35, vcc, 0, v19, vcc
	v_add_co_u32_e32 v94, vcc, s0, v18
	s_mov_b32 s0, 0x1f000
	s_nop 0
	v_addc_co_u32_e32 v95, vcc, 0, v19, vcc
	v_add_co_u32_e32 v108, vcc, s0, v18
	s_mov_b32 s0, 0x20000
	s_nop 0
	v_addc_co_u32_e32 v109, vcc, 0, v19, vcc
	v_add_co_u32_e32 v100, vcc, s0, v18
	s_mov_b32 s0, 0x1e000
	s_nop 0
	v_addc_co_u32_e32 v101, vcc, 0, v19, vcc
	v_add_co_u32_e32 v52, vcc, s0, v18
	s_mov_b32 s0, 0x1b000
	s_nop 0
	v_addc_co_u32_e32 v53, vcc, 0, v19, vcc
	v_add_co_u32_e32 v92, vcc, s0, v18
	s_mov_b32 s0, 0x19000
	s_nop 0
	v_addc_co_u32_e32 v93, vcc, 0, v19, vcc
	global_load_dwordx2 v[104:105], v[20:21], off offset:1024
	global_load_dwordx2 v[106:107], v[20:21], off offset:3072
	v_add_co_u32_e32 v110, vcc, s0, v18
	global_load_dwordx2 v[98:99], v[32:33], off offset:2048
	s_nop 0
	v_addc_co_u32_e32 v111, vcc, 0, v19, vcc
	v_add_co_u32_e32 v112, vcc, s81, v18
	s_mov_b32 s0, 0x22000
	s_nop 0
	v_addc_co_u32_e32 v113, vcc, 0, v19, vcc
	global_load_dwordx2 v[62:63], v[52:53], off offset:2048
	global_load_dwordx2 v[96:97], v[92:93], off offset:3072
	global_load_dwordx2 v[136:137], v[110:111], off
	global_load_dwordx2 v[138:139], v[112:113], off offset:1024
	global_load_dwordx2 v[140:141], v[32:33], off
	global_load_dwordx2 v[142:143], v[20:21], off offset:2048
	v_add_co_u32_e32 v54, vcc, s0, v18
	s_mov_b32 s0, 0x25000
	s_nop 0
	v_addc_co_u32_e32 v55, vcc, 0, v19, vcc
	v_add_co_u32_e32 v48, vcc, s0, v18
	s_mov_b32 s0, 0x27000
	s_nop 0
	v_addc_co_u32_e32 v49, vcc, 0, v19, vcc
	v_add_co_u32_e32 v38, vcc, s0, v18
	s_mov_b32 s0, 0x28000
	s_nop 0
	v_addc_co_u32_e32 v39, vcc, 0, v19, vcc
	v_add_co_u32_e32 v42, vcc, s0, v18
	s_mov_b32 s0, 0x2a000
	s_nop 0
	v_addc_co_u32_e32 v43, vcc, 0, v19, vcc
	v_add_co_u32_e32 v22, vcc, s0, v18
	s_mov_b32 s0, 0x2b000
	s_nop 0
	v_addc_co_u32_e32 v23, vcc, 0, v19, vcc
	v_add_co_u32_e32 v24, vcc, s0, v18
	s_mov_b32 s0, 0x29000
	s_nop 0
	v_addc_co_u32_e32 v25, vcc, 0, v19, vcc
	v_add_co_u32_e32 v20, vcc, s0, v18
	s_mov_b32 s0, 0x26000
	s_nop 0
	v_addc_co_u32_e32 v21, vcc, 0, v19, vcc
	v_add_co_u32_e32 v30, vcc, s0, v18
	s_mov_b32 s0, 0x24000
	s_nop 0
	v_addc_co_u32_e32 v31, vcc, 0, v19, vcc
	global_load_dwordx2 v[36:37], v[42:43], off offset:1024
	global_load_dwordx2 v[28:29], v[22:23], off offset:2048
	s_nop 0
	global_load_dwordx2 v[24:25], v[24:25], off
	s_nop 0
	global_load_dwordx2 v[22:23], v[22:23], off offset:3072
	v_add_co_u32_e32 v40, vcc, s0, v18
	global_load_dwordx2 v[144:145], v[34:35], off offset:3072
	global_load_dwordx2 v[146:147], v[94:95], off
	global_load_dwordx2 v[148:149], v[32:33], off offset:1024
	global_load_dwordx2 v[46:47], v[48:49], off offset:2048
	s_nop 0
	global_load_dwordx2 v[38:39], v[38:39], off offset:3072
	s_nop 0
	global_load_dwordx2 v[32:33], v[42:43], off
	s_nop 0
	global_load_dwordx2 v[42:43], v[48:49], off offset:1024
	v_addc_co_u32_e32 v41, vcc, 0, v19, vcc
	s_mov_b32 s0, 0x21000
	v_add_co_u32_e32 v50, vcc, s0, v18
	v_pk_fma_f32 v[58:59], v[2:3], v[60:61], v[58:59]
	s_nop 0
	v_addc_co_u32_e32 v51, vcc, 0, v19, vcc
	global_load_dwordx2 v[18:19], v[20:21], off offset:2048
	global_load_dwordx2 v[34:35], v[30:31], off offset:3072
	global_load_dwordx2 v[44:45], v[40:41], off
	global_load_dwordx2 v[56:57], v[50:51], off offset:1024
	global_load_dwordx2 v[90:91], v[54:55], off offset:1024
	global_load_dwordx2 v[64:65], v[54:55], off offset:3072
	s_nop 0
	global_load_dwordx2 v[48:49], v[48:49], off
	s_nop 0
	global_load_dwordx2 v[54:55], v[54:55], off offset:2048
	s_nop 0
	global_load_dwordx2 v[150:151], v[94:95], off offset:1024
	global_load_dwordx2 v[102:103], v[108:109], off offset:2048
	s_nop 0
	global_load_dwordx2 v[100:101], v[100:101], off
	s_nop 0
	global_load_dwordx2 v[94:95], v[108:109], off offset:3072
	v_pk_fma_f32 v[66:67], v[4:5], v[88:89], v[66:67]
	v_pk_fma_f32 v[60:61], v[10:11], v[60:61], v[14:15]
	v_pk_fma_f32 v[88:89], v[12:13], v[88:89], v[16:17]
	s_mov_b64 s[0:1], 0
	s_waitcnt vmcnt(31)
	v_lshlrev_b32_e32 v108, 16, v104
	v_and_b32_e32 v109, 0xffff0000, v104
	s_waitcnt vmcnt(30)
	v_lshlrev_b32_e32 v152, 16, v106
	v_and_b32_e32 v153, 0xffff0000, v106
	v_pk_mul_f32 v[108:109], v[108:109], v[152:153]
	v_lshlrev_b32_e32 v104, 16, v105
	v_and_b32_e32 v105, 0xffff0000, v105
	v_lshlrev_b32_e32 v106, 16, v107
	v_and_b32_e32 v107, 0xffff0000, v107
	v_pk_mul_f32 v[104:105], v[104:105], v[106:107]
	s_waitcnt vmcnt(25)
	v_lshlrev_b32_e32 v152, 16, v138
	v_and_b32_e32 v153, 0xffff0000, v138
	v_pk_mul_f32 v[154:155], v[152:153], s[24:25] op_sel_hi:[1,0]
	v_lshlrev_b32_e32 v138, 16, v139
	v_and_b32_e32 v139, 0xffff0000, v139
	v_exp_f32_e32 v154, v154
	v_exp_f32_e32 v155, v155
	v_pk_mul_f32 v[156:157], v[138:139], s[24:25] op_sel_hi:[1,0]
	v_pk_fma_f32 v[58:59], v[6:7], v[108:109], v[58:59]
	v_exp_f32_e32 v156, v156
	v_exp_f32_e32 v157, v157
	v_pk_add_f32 v[154:155], v[154:155], 1.0 op_sel_hi:[1,0]
	s_waitcnt vmcnt(23)
	v_lshlrev_b32_e32 v106, 16, v142
	v_rcp_f32_e32 v154, v154
	v_rcp_f32_e32 v155, v155
	v_pk_add_f32 v[156:157], v[156:157], 1.0 op_sel_hi:[1,0]
	v_and_b32_e32 v107, 0xffff0000, v142
	v_rcp_f32_e32 v156, v156
	v_rcp_f32_e32 v157, v157
	v_pk_fma_f32 v[66:67], v[8:9], v[104:105], v[66:67]
	v_lshlrev_b32_e32 v142, 16, v143
	v_and_b32_e32 v143, 0xffff0000, v143
	v_pk_mul_f32 v[152:153], v[154:155], v[152:153]
	v_pk_mul_f32 v[58:59], v[58:59], v[106:107]
	v_pk_mul_f32 v[138:139], v[156:157], v[138:139]
	v_pk_mul_f32 v[66:67], v[66:67], v[142:143]
	v_pk_mul_f32 v[58:59], v[58:59], v[152:153]
	v_lshlrev_b32_e32 v106, 16, v136
	v_and_b32_e32 v107, 0xffff0000, v136
	v_pk_mul_f32 v[66:67], v[66:67], v[138:139]
	v_cvt_pk_bf16_f32 v58, v58, v59
	v_lshlrev_b32_e32 v136, 16, v137
	v_cvt_pk_bf16_f32 v59, v66, v67
	global_store_dwordx2 v[112:113], v[58:59], off offset:1024
	v_pk_mul_f32 v[112:113], v[106:107], s[24:25] op_sel_hi:[1,0]
	v_and_b32_e32 v137, 0xffff0000, v137
	v_exp_f32_e32 v112, v112
	v_exp_f32_e32 v113, v113
	v_pk_mul_f32 v[138:139], v[136:137], s[24:25] op_sel_hi:[1,0]
	v_lshlrev_b32_e32 v58, 16, v140
	v_exp_f32_e32 v138, v138
	v_exp_f32_e32 v139, v139
	v_pk_add_f32 v[112:113], v[112:113], 1.0 op_sel_hi:[1,0]
	v_and_b32_e32 v59, 0xffff0000, v140
	v_rcp_f32_e32 v112, v112
	v_rcp_f32_e32 v113, v113
	v_pk_add_f32 v[138:139], v[138:139], 1.0 op_sel_hi:[1,0]
	v_lshlrev_b32_e32 v66, 16, v98
	v_and_b32_e32 v67, 0xffff0000, v98
	v_rcp_f32_e32 v138, v138
	v_rcp_f32_e32 v139, v139
	v_pk_mul_f32 v[58:59], v[58:59], v[66:67]
	v_lshlrev_b32_e32 v66, 16, v141
	v_and_b32_e32 v67, 0xffff0000, v141
	v_lshlrev_b32_e32 v98, 16, v99
	v_and_b32_e32 v99, 0xffff0000, v99
	v_pk_fma_f32 v[60:61], v[2:3], v[108:109], v[60:61]
	v_pk_mul_f32 v[66:67], v[66:67], v[98:99]
	v_pk_fma_f32 v[88:89], v[4:5], v[104:105], v[88:89]
	v_pk_fma_f32 v[60:61], v[6:7], v[58:59], v[60:61]
	s_waitcnt vmcnt(17)
	v_lshlrev_b32_e32 v98, 16, v148
	v_and_b32_e32 v99, 0xffff0000, v148
	v_pk_fma_f32 v[88:89], v[8:9], v[66:67], v[88:89]
	v_lshlrev_b32_e32 v140, 16, v149
	v_and_b32_e32 v141, 0xffff0000, v149
	v_pk_mul_f32 v[106:107], v[112:113], v[106:107]
	v_pk_mul_f32 v[60:61], v[60:61], v[98:99]
	v_pk_mul_f32 v[112:113], v[138:139], v[136:137]
	v_pk_mul_f32 v[88:89], v[88:89], v[140:141]
	v_pk_mul_f32 v[60:61], v[60:61], v[106:107]
	v_pk_mul_f32 v[88:89], v[88:89], v[112:113]
	v_cvt_pk_bf16_f32 v60, v60, v61
	s_waitcnt vmcnt(4)
	v_lshlrev_b32_e32 v98, 16, v151
	v_cvt_pk_bf16_f32 v61, v88, v89
	global_store_dwordx2 v[110:111], v[60:61], off
	v_lshlrev_b32_e32 v60, 16, v144
	v_and_b32_e32 v61, 0xffff0000, v144
	v_lshlrev_b32_e32 v88, 16, v150
	v_and_b32_e32 v89, 0xffff0000, v150
	v_pk_mul_f32 v[60:61], v[60:61], v[88:89]
	v_lshlrev_b32_e32 v88, 16, v145
	v_and_b32_e32 v89, 0xffff0000, v145
	v_and_b32_e32 v99, 0xffff0000, v151
	v_pk_mul_f32 v[88:89], v[88:89], v[98:99]
	v_pk_fma_f32 v[98:99], v[12:13], v[104:105], v[16:17]
	v_pk_fma_f32 v[104:105], v[10:11], v[108:109], v[14:15]
	v_lshlrev_b32_e32 v108, 16, v96
	v_and_b32_e32 v109, 0xffff0000, v96
	v_lshlrev_b32_e32 v96, 16, v97
	v_and_b32_e32 v97, 0xffff0000, v97
	v_pk_mul_f32 v[110:111], v[108:109], s[24:25] op_sel_hi:[1,0]
	v_pk_mul_f32 v[112:113], v[96:97], s[24:25] op_sel_hi:[1,0]
	v_exp_f32_e32 v110, v110
	v_exp_f32_e32 v111, v111
	v_exp_f32_e32 v112, v112
	v_exp_f32_e32 v113, v113
	v_pk_fma_f32 v[104:105], v[2:3], v[58:59], v[104:105]
	v_pk_add_f32 v[110:111], v[110:111], 1.0 op_sel_hi:[1,0]
	v_pk_fma_f32 v[98:99], v[4:5], v[66:67], v[98:99]
	v_pk_add_f32 v[112:113], v[112:113], 1.0 op_sel_hi:[1,0]
	v_rcp_f32_e32 v110, v110
	v_rcp_f32_e32 v111, v111
	v_rcp_f32_e32 v112, v112
	v_rcp_f32_e32 v113, v113
	v_pk_fma_f32 v[98:99], v[8:9], v[88:89], v[98:99]
	v_pk_fma_f32 v[104:105], v[6:7], v[60:61], v[104:105]
	v_lshlrev_b32_e32 v106, 16, v146
	v_and_b32_e32 v107, 0xffff0000, v146
	v_lshlrev_b32_e32 v136, 16, v147
	v_and_b32_e32 v137, 0xffff0000, v147
	v_pk_mul_f32 v[108:109], v[110:111], v[108:109]
	v_pk_mul_f32 v[96:97], v[112:113], v[96:97]
	v_pk_mul_f32 v[104:105], v[104:105], v[106:107]
	v_pk_mul_f32 v[98:99], v[98:99], v[136:137]
	v_pk_fma_f32 v[58:59], v[10:11], v[58:59], v[14:15]
	v_pk_mul_f32 v[96:97], v[98:99], v[96:97]
	v_pk_mul_f32 v[98:99], v[104:105], v[108:109]
	v_pk_fma_f32 v[66:67], v[12:13], v[66:67], v[16:17]
	v_cvt_pk_bf16_f32 v98, v98, v99
	v_cvt_pk_bf16_f32 v99, v96, v97
	global_store_dwordx2 v[92:93], v[98:99], off offset:3072
	s_waitcnt vmcnt(5)
	v_lshlrev_b32_e32 v92, 16, v102
	v_and_b32_e32 v93, 0xffff0000, v102
	s_waitcnt vmcnt(4)
	v_lshlrev_b32_e32 v96, 16, v100
	v_and_b32_e32 v97, 0xffff0000, v100
	v_lshlrev_b32_e32 v98, 16, v101
	v_and_b32_e32 v99, 0xffff0000, v101
	v_lshlrev_b32_e32 v100, 16, v62
	v_and_b32_e32 v101, 0xffff0000, v62
	v_pk_mul_f32 v[92:93], v[92:93], v[96:97]
	v_lshlrev_b32_e32 v96, 16, v103
	v_and_b32_e32 v97, 0xffff0000, v103
	v_pk_mul_f32 v[102:103], v[100:101], s[24:25] op_sel_hi:[1,0]
	v_lshlrev_b32_e32 v62, 16, v63
	v_and_b32_e32 v63, 0xffff0000, v63
	v_exp_f32_e32 v102, v102
	v_exp_f32_e32 v103, v103
	v_pk_mul_f32 v[104:105], v[62:63], s[24:25] op_sel_hi:[1,0]
	v_pk_fma_f32 v[58:59], v[2:3], v[60:61], v[58:59]
	v_exp_f32_e32 v104, v104
	v_exp_f32_e32 v105, v105
	v_pk_add_f32 v[102:103], v[102:103], 1.0 op_sel_hi:[1,0]
	v_pk_mul_f32 v[96:97], v[96:97], v[98:99]
	v_rcp_f32_e32 v102, v102
	v_rcp_f32_e32 v103, v103
	v_pk_add_f32 v[104:105], v[104:105], 1.0 op_sel_hi:[1,0]
	v_pk_fma_f32 v[66:67], v[4:5], v[88:89], v[66:67]
	v_rcp_f32_e32 v104, v104
	v_rcp_f32_e32 v105, v105
	v_pk_fma_f32 v[58:59], v[6:7], v[92:93], v[58:59]
	s_waitcnt vmcnt(3)
	v_lshlrev_b32_e32 v98, 16, v94
	v_and_b32_e32 v99, 0xffff0000, v94
	v_pk_fma_f32 v[66:67], v[8:9], v[96:97], v[66:67]
	v_lshlrev_b32_e32 v94, 16, v95
	v_and_b32_e32 v95, 0xffff0000, v95
	v_pk_mul_f32 v[100:101], v[102:103], v[100:101]
	v_pk_mul_f32 v[58:59], v[58:59], v[98:99]
	v_pk_mul_f32 v[62:63], v[104:105], v[62:63]
	v_pk_mul_f32 v[66:67], v[66:67], v[94:95]
	v_pk_mul_f32 v[58:59], v[58:59], v[100:101]
	v_pk_mul_f32 v[62:63], v[66:67], v[62:63]
	v_cvt_pk_bf16_f32 v58, v58, v59
	v_lshlrev_b32_e32 v66, 16, v56
	v_cvt_pk_bf16_f32 v59, v62, v63
	global_store_dwordx2 v[52:53], v[58:59], off offset:2048
	v_lshlrev_b32_e32 v52, 16, v90
	v_and_b32_e32 v53, 0xffff0000, v90
	v_lshlrev_b32_e32 v58, 16, v64
	v_and_b32_e32 v59, 0xffff0000, v64
	v_pk_mul_f32 v[52:53], v[52:53], v[58:59]
	v_lshlrev_b32_e32 v58, 16, v91
	v_and_b32_e32 v59, 0xffff0000, v91
	v_lshlrev_b32_e32 v62, 16, v65
	v_and_b32_e32 v63, 0xffff0000, v65
	v_and_b32_e32 v67, 0xffff0000, v56
	v_lshlrev_b32_e32 v56, 16, v57
	v_and_b32_e32 v57, 0xffff0000, v57
	v_pk_mul_f32 v[58:59], v[58:59], v[62:63]
	v_pk_fma_f32 v[62:63], v[12:13], v[88:89], v[16:17]
	v_pk_mul_f32 v[88:89], v[66:67], s[24:25] op_sel_hi:[1,0]
	v_pk_mul_f32 v[90:91], v[56:57], s[24:25] op_sel_hi:[1,0]
	v_exp_f32_e32 v88, v88
	v_exp_f32_e32 v89, v89
	v_exp_f32_e32 v90, v90
	v_exp_f32_e32 v91, v91
	v_pk_fma_f32 v[60:61], v[10:11], v[60:61], v[14:15]
	v_pk_add_f32 v[88:89], v[88:89], 1.0 op_sel_hi:[1,0]
	v_pk_fma_f32 v[60:61], v[2:3], v[92:93], v[60:61]
	v_pk_add_f32 v[90:91], v[90:91], 1.0 op_sel_hi:[1,0]
	v_rcp_f32_e32 v88, v88
	v_rcp_f32_e32 v89, v89
	v_rcp_f32_e32 v90, v90
	v_rcp_f32_e32 v91, v91
	v_pk_fma_f32 v[62:63], v[4:5], v[96:97], v[62:63]
	v_pk_fma_f32 v[60:61], v[6:7], v[52:53], v[60:61]
	v_pk_fma_f32 v[62:63], v[8:9], v[58:59], v[62:63]
	v_lshlrev_b32_e32 v64, 16, v54
	v_and_b32_e32 v65, 0xffff0000, v54
	v_lshlrev_b32_e32 v54, 16, v55
	v_and_b32_e32 v55, 0xffff0000, v55
	v_pk_mul_f32 v[66:67], v[88:89], v[66:67]
	v_pk_mul_f32 v[56:57], v[90:91], v[56:57]
	v_pk_mul_f32 v[60:61], v[60:61], v[64:65]
	v_pk_mul_f32 v[54:55], v[62:63], v[54:55]
	s_nop 0
	v_pk_mul_f32 v[54:55], v[54:55], v[56:57]
	v_pk_mul_f32 v[56:57], v[60:61], v[66:67]
	v_lshlrev_b32_e32 v60, 16, v44
	v_and_b32_e32 v61, 0xffff0000, v44
	v_lshlrev_b32_e32 v44, 16, v45
	v_and_b32_e32 v45, 0xffff0000, v45
	v_pk_mul_f32 v[62:63], v[60:61], s[24:25] op_sel_hi:[1,0]
	v_pk_mul_f32 v[64:65], v[44:45], s[24:25] op_sel_hi:[1,0]
	v_exp_f32_e32 v62, v62
	v_exp_f32_e32 v63, v63
	v_exp_f32_e32 v64, v64
	v_exp_f32_e32 v65, v65
	v_cvt_pk_bf16_f32 v56, v56, v57
	v_pk_add_f32 v[62:63], v[62:63], 1.0 op_sel_hi:[1,0]
	v_cvt_pk_bf16_f32 v57, v54, v55
	v_pk_add_f32 v[64:65], v[64:65], 1.0 op_sel_hi:[1,0]
	global_store_dwordx2 v[50:51], v[56:57], off offset:1024
	v_lshlrev_b32_e32 v50, 16, v48
	v_and_b32_e32 v51, 0xffff0000, v48
	v_lshlrev_b32_e32 v54, 16, v46
	v_and_b32_e32 v55, 0xffff0000, v46
	v_lshlrev_b32_e32 v48, 16, v49
	v_and_b32_e32 v49, 0xffff0000, v49
	v_lshlrev_b32_e32 v46, 16, v47
	v_and_b32_e32 v47, 0xffff0000, v47
	v_rcp_f32_e32 v62, v62
	v_rcp_f32_e32 v63, v63
	v_rcp_f32_e32 v64, v64
	v_rcp_f32_e32 v65, v65
	v_pk_mul_f32 v[50:51], v[50:51], v[54:55]
	v_pk_mul_f32 v[46:47], v[48:49], v[46:47]
	v_pk_fma_f32 v[48:49], v[12:13], v[96:97], v[16:17]
	v_pk_fma_f32 v[54:55], v[10:11], v[92:93], v[14:15]
	v_pk_fma_f32 v[48:49], v[4:5], v[58:59], v[48:49]
	v_pk_fma_f32 v[54:55], v[2:3], v[52:53], v[54:55]
	v_pk_fma_f32 v[48:49], v[8:9], v[46:47], v[48:49]
	v_pk_fma_f32 v[54:55], v[6:7], v[50:51], v[54:55]
	v_lshlrev_b32_e32 v56, 16, v42
	v_and_b32_e32 v57, 0xffff0000, v42
	v_lshlrev_b32_e32 v42, 16, v43
	v_and_b32_e32 v43, 0xffff0000, v43
	v_pk_mul_f32 v[60:61], v[62:63], v[60:61]
	v_pk_mul_f32 v[44:45], v[64:65], v[44:45]
	v_pk_mul_f32 v[54:55], v[54:55], v[56:57]
	v_pk_mul_f32 v[42:43], v[48:49], v[42:43]
	v_lshlrev_b32_e32 v48, 16, v34
	v_pk_mul_f32 v[42:43], v[42:43], v[44:45]
	v_pk_mul_f32 v[44:45], v[54:55], v[60:61]
	v_and_b32_e32 v49, 0xffff0000, v34
	v_cvt_pk_bf16_f32 v44, v44, v45
	v_cvt_pk_bf16_f32 v45, v42, v43
	global_store_dwordx2 v[40:41], v[44:45], off
	v_lshlrev_b32_e32 v40, 16, v38
	v_and_b32_e32 v41, 0xffff0000, v38
	v_lshlrev_b32_e32 v42, 16, v36
	v_and_b32_e32 v43, 0xffff0000, v36
	v_lshlrev_b32_e32 v34, 16, v35
	v_and_b32_e32 v35, 0xffff0000, v35
	v_pk_mul_f32 v[40:41], v[40:41], v[42:43]
	v_pk_fma_f32 v[42:43], v[10:11], v[52:53], v[14:15]
	v_pk_mul_f32 v[52:53], v[48:49], s[24:25] op_sel_hi:[1,0]
	v_pk_mul_f32 v[54:55], v[34:35], s[24:25] op_sel_hi:[1,0]
	v_exp_f32_e32 v52, v52
	v_exp_f32_e32 v53, v53
	v_exp_f32_e32 v54, v54
	v_exp_f32_e32 v55, v55
	v_lshlrev_b32_e32 v38, 16, v39
	v_pk_add_f32 v[52:53], v[52:53], 1.0 op_sel_hi:[1,0]
	v_and_b32_e32 v39, 0xffff0000, v39
	v_pk_add_f32 v[54:55], v[54:55], 1.0 op_sel_hi:[1,0]
	v_lshlrev_b32_e32 v36, 16, v37
	v_and_b32_e32 v37, 0xffff0000, v37
	v_rcp_f32_e32 v52, v52
	v_rcp_f32_e32 v53, v53
	v_rcp_f32_e32 v54, v54
	v_rcp_f32_e32 v55, v55
	v_pk_mul_f32 v[36:37], v[38:39], v[36:37]
	v_pk_fma_f32 v[38:39], v[12:13], v[58:59], v[16:17]
	v_pk_fma_f32 v[42:43], v[2:3], v[50:51], v[42:43]
	v_pk_fma_f32 v[38:39], v[4:5], v[46:47], v[38:39]
	v_pk_fma_f32 v[42:43], v[6:7], v[40:41], v[42:43]
	v_pk_fma_f32 v[38:39], v[8:9], v[36:37], v[38:39]
	v_lshlrev_b32_e32 v44, 16, v32
	v_and_b32_e32 v45, 0xffff0000, v32
	v_lshlrev_b32_e32 v32, 16, v33
	v_and_b32_e32 v33, 0xffff0000, v33
	v_pk_mul_f32 v[48:49], v[52:53], v[48:49]
	v_pk_mul_f32 v[34:35], v[54:55], v[34:35]
	v_pk_mul_f32 v[42:43], v[42:43], v[44:45]
	v_pk_mul_f32 v[32:33], v[38:39], v[32:33]
	v_pk_fma_f32 v[12:13], v[12:13], v[46:47], v[16:17]
	v_pk_mul_f32 v[32:33], v[32:33], v[34:35]
	v_pk_mul_f32 v[34:35], v[42:43], v[48:49]
	v_pk_fma_f32 v[4:5], v[4:5], v[36:37], v[12:13]
	v_cvt_pk_bf16_f32 v34, v34, v35
	v_cvt_pk_bf16_f32 v35, v32, v33
	global_store_dwordx2 v[30:31], v[34:35], off offset:3072
	v_lshlrev_b32_e32 v30, 16, v28
	v_and_b32_e32 v31, 0xffff0000, v28
	v_lshlrev_b32_e32 v32, 16, v24
	v_and_b32_e32 v33, 0xffff0000, v24
	v_lshlrev_b32_e32 v28, 16, v29
	v_and_b32_e32 v29, 0xffff0000, v29
	v_lshlrev_b32_e32 v24, 16, v25
	v_and_b32_e32 v25, 0xffff0000, v25
	v_pk_mul_f32 v[24:25], v[28:29], v[24:25]
	v_pk_fma_f32 v[10:11], v[10:11], v[50:51], v[14:15]
	v_pk_fma_f32 v[4:5], v[8:9], v[24:25], v[4:5]
	v_lshlrev_b32_e32 v8, 16, v18
	v_and_b32_e32 v9, 0xffff0000, v18
	v_pk_fma_f32 v[2:3], v[2:3], v[40:41], v[10:11]
	v_pk_mul_f32 v[10:11], v[8:9], s[24:25] op_sel_hi:[1,0]
	v_lshlrev_b32_e32 v12, 16, v19
	v_and_b32_e32 v13, 0xffff0000, v19
	v_exp_f32_e32 v10, v10
	v_exp_f32_e32 v11, v11
	v_pk_mul_f32 v[14:15], v[12:13], s[24:25] op_sel_hi:[1,0]
	v_pk_mul_f32 v[30:31], v[30:31], v[32:33]
	v_exp_f32_e32 v14, v14
	v_exp_f32_e32 v15, v15
	v_pk_add_f32 v[10:11], v[10:11], 1.0 op_sel_hi:[1,0]
	v_pk_fma_f32 v[2:3], v[6:7], v[30:31], v[2:3]
	v_rcp_f32_e32 v10, v10
	v_rcp_f32_e32 v11, v11
	v_pk_add_f32 v[14:15], v[14:15], 1.0 op_sel_hi:[1,0]
	v_lshlrev_b32_e32 v6, 16, v22
	v_rcp_f32_e32 v14, v14
	v_rcp_f32_e32 v15, v15
	v_and_b32_e32 v7, 0xffff0000, v22
	v_lshlrev_b32_e32 v16, 16, v23
	v_and_b32_e32 v17, 0xffff0000, v23
	v_pk_mul_f32 v[8:9], v[10:11], v[8:9]
	v_pk_mul_f32 v[2:3], v[2:3], v[6:7]
	v_pk_mul_f32 v[10:11], v[14:15], v[12:13]
	v_pk_mul_f32 v[4:5], v[4:5], v[16:17]
	v_pk_mul_f32 v[2:3], v[2:3], v[8:9]
	v_pk_mul_f32 v[4:5], v[4:5], v[10:11]
	v_cvt_pk_bf16_f32 v2, v2, v3
	s_nop 0
	v_cvt_pk_bf16_f32 v3, v4, v5
	global_store_dwordx2 v[20:21], v[2:3], off offset:2048

.LBB0_765:
	v_readlane_b32 s16, v252, 37
	v_readlane_b32 s17, v252, 38
	s_mov_b64 s[20:21], -1
	s_mov_b64 s[26:27], -1
	s_waitcnt lgkmcnt(0)
	s_nop 4
	global_load_dword v2, v27, s[16:17] sc1
	global_load_dword v3, v27, s[16:17] offset:256 sc1
	global_load_dword v4, v27, s[16:17] offset:512 sc1
	global_load_dword v5, v27, s[16:17] offset:768 sc1
	global_load_dword v6, v27, s[16:17] offset:1024 sc1
	global_load_dword v7, v27, s[16:17] offset:1280 sc1
	global_load_dword v8, v27, s[16:17] offset:1536 sc1
	global_load_dword v9, v27, s[16:17] offset:1792 sc1
	global_load_dword v10, v27, s[16:17] offset:2048 sc1
	global_load_dword v11, v27, s[16:17] offset:2304 sc1
	global_load_dword v12, v27, s[16:17] offset:2560 sc1
	global_load_dword v13, v27, s[16:17] offset:2816 sc1
	global_load_dword v14, v27, s[16:17] offset:3072 sc1
	global_load_dword v15, v27, s[16:17] offset:3328 sc1
	global_load_dword v16, v27, s[16:17] offset:3584 sc1
	global_load_dword v17, v27, s[16:17] offset:3840 sc1
	s_waitcnt vmcnt(0)
	v_add_u32_e32 v18, v3, v2
	v_add_u32_e32 v18, v18, v4
	v_add_u32_e32 v18, v18, v5
	v_add_u32_e32 v18, v18, v6
	v_add_u32_e32 v18, v18, v7
	v_add_u32_e32 v18, v18, v8
	v_add_u32_e32 v18, v18, v9
	v_add_u32_e32 v18, v18, v10
	v_add_u32_e32 v18, v18, v11
	v_add_u32_e32 v18, v18, v12
	v_add_u32_e32 v18, v18, v13
	v_add_u32_e32 v18, v18, v14
	v_add_u32_e32 v18, v18, v15
	v_add_u32_e32 v18, v18, v16
	v_add_u32_e32 v18, v18, v17
	v_cmp_eq_u32_e32 vcc, s4, v18
	s_cbranch_vccnz .LBB0_764
	s_and_b32 s11, s8, 0xff
	s_cmp_eq_u32 s11, 0
	s_mov_b64 s[28:29], -1
	s_sleep 1
	s_cbranch_scc0 .LBB0_769
	v_readlane_b32 s16, v252, 35
	v_readlane_b32 s17, v252, 36
	s_nop 4
	global_load_dword v18, v27, s[16:17] sc1
	s_waitcnt vmcnt(0)
	v_cmp_eq_u32_e32 vcc, 0, v18
	s_cbranch_vccnz .LBB0_771
	s_mov_b64 s[28:29], 0
